# F2 selects away the neighbouring batch halo (no NaN*0), so F1->F2 barrier is XCD-local except in the last layer (27 of 36 local)
# speedup vs baseline: 1.0084x; 1.0084x over previous
; __device__ __forceinline__ unsigned cvt_pk_bf16(float lo, float hi) { unsigned r; asm volatile("v_cvt_pk_bf16_f32 %0, %1, %2" : "=v"(r) : "v"(lo), "v"(hi)); return r; }
; __device__ __forceinline__ void phase_ffn_fix(const Frame& F, const float* cw, const float* cb) {
;     ...
;     for (int it = (byx ? F.rank : F.bx) * NTHREADS + F.tid; it < (byx ? TOT / 8 : TOT); it += (byx ? 32 : F.G) * NTHREADS) {
;         const int cgi = it % CG, rr = (it / CG) & 1, chunk = (byx ? F.xcd * 64 : 0) + it / (2 * CG), col = 4 * cgi;
;         const int prev = chunk > 0 ? chunk - 1 : 0; const float hm = (chunk & 63) ? 1.0f : 0.0f;
;         f32x4 cv = *(const f32x4*)(part + (size_t)(chunk * 2 + rr) * D_FF + col);
;         const f32x4 v = *(const f32x4*)(val01 + (size_t)(chunk * 2 + rr) * D_FF + col);
;         const f32x4 h0 = *(const f32x4*)(halo + (size_t)(prev * 2 + 0) * D_FF + col), h1 = *(const f32x4*)(halo + (size_t)(prev * 2 + 1) * D_FF + col);
;         const f32x4 w0 = *(const f32x4*)(cw + col), w1 = *(const f32x4*)(cw + D_FF + col);
;         const f32x4 add = (rr == 0) ? (w1 * h1 + w0 * h0) : (w0 * h1);
;         cv = cv + add * hm;
;         u32x2 w; w.x = cvt_pk_bf16(gelu_tanh(cv[0]) * v[0], gelu_tanh(cv[1]) * v[1]); w.y = cvt_pk_bf16(gelu_tanh(cv[2]) * v[2], gelu_tanh(cv[3]) * v[3]);
;         *(u32x2*)(act + (size_t)(chunk * 64 + rr) * D_FF + col) = w;
.LBB0_51:
	s_or_b64 exec, exec, s[26:27]
	s_waitcnt vmcnt(1)
	v_and_b32_e32 v12, 63, v28
	v_cmp_eq_u32_e32 vcc, 0, v12
	s_movk_i32 s26, 0x1600
	v_add_u32_e32 v24, s30, v24
	v_cndmask_b32_e64 v12, 1.0, 0, vcc
	v_cndmask_b32_e32 v8, v8, v165, vcc
	v_cndmask_b32_e32 v9, v9, v165, vcc
	v_cndmask_b32_e32 v10, v10, v165, vcc
	v_cndmask_b32_e32 v11, v11, v165, vcc
	v_pk_fma_f32 v[4:5], v[12:13], v[8:9], v[4:5] op_sel_hi:[0,1,1]
	v_mul_f32_e32 v8, 0x3d372713, v4
	v_mul_f32_e32 v8, v4, v8
	v_mul_f32_e32 v9, 0x3d372713, v5
	v_fma_f32 v8, v4, v8, v4
	v_mul_f32_e32 v9, v5, v9
	v_mul_f32_e32 v8, 0x3f4c422a, v8
	v_fma_f32 v9, v5, v9, v5
	v_mul_f32_e32 v8, 0xc038aa3b, v8
	v_mul_f32_e32 v9, 0x3f4c422a, v9
	v_exp_f32_e32 v8, v8
	v_mul_f32_e32 v9, 0xc038aa3b, v9
	v_exp_f32_e32 v9, v9
	v_pk_fma_f32 v[6:7], v[12:13], v[10:11], v[6:7] op_sel_hi:[0,1,1]
	v_add_f32_e32 v8, 1.0, v8
	v_rcp_f32_e32 v8, v8
	v_add_f32_e32 v9, 1.0, v9
	v_rcp_f32_e32 v9, v9
	v_cmp_le_i32_e32 vcc, s28, v24
	v_mul_f32_e32 v4, v4, v8
	v_mul_f32_e32 v0, v0, v4
	v_mul_f32_e32 v4, v5, v9
	v_mul_f32_e32 v5, 0x3d372713, v6
	v_mul_f32_e32 v5, v6, v5
	v_mul_f32_e32 v8, 0x3d372713, v7
	v_fma_f32 v5, v6, v5, v6
	v_mul_f32_e32 v8, v7, v8
	v_mul_f32_e32 v5, 0x3f4c422a, v5
	v_fma_f32 v8, v7, v8, v7
	v_mul_f32_e32 v5, 0xc038aa3b, v5
	v_mul_f32_e32 v8, 0x3f4c422a, v8
	v_exp_f32_e32 v5, v5
	v_mul_f32_e32 v8, 0xc038aa3b, v8
	v_exp_f32_e32 v8, v8
	v_mul_f32_e32 v1, v1, v4
	v_add_f32_e32 v4, 1.0, v5
	v_rcp_f32_e32 v4, v4
	v_add_f32_e32 v5, 1.0, v8
	v_rcp_f32_e32 v5, v5
	v_cvt_pk_bf16_f32 v0, v0, v1
	v_mul_f32_e32 v1, v6, v4
	v_mul_f32_e32 v1, v2, v1
	v_mul_f32_e32 v2, v7, v5
	v_mul_f32_e32 v2, v3, v2
	v_cvt_pk_bf16_f32 v1, v1, v2
	v_lshl_or_b32 v4, v27, 6, v26
	v_mov_b64_e32 v[2:3], s[0:1]
	v_mad_i64_i32 v[2:3], s[26:27], v4, s26, v[2:3]
	v_lshl_add_u64 v[2:3], v[20:21], 1, v[2:3]
	s_or_b64 s[6:7], vcc, s[6:7]
	v_add_u32_e32 v25, s31, v25
	global_store_dwordx2 v[2:3], v[0:1], off
	s_andn2_b64 exec, exec, s[6:7]
	s_cbranch_execz .LBB0_56

; #define LAS __attribute__((address_space(3)))
; __device__ __forceinline__ unsigned xb_ld(unsigned* p)              { return __hip_atomic_load(p, __ATOMIC_RELAXED, __HIP_MEMORY_SCOPE_AGENT); }
; __device__ __forceinline__ unsigned xb_xcc_id() { return (unsigned)__builtin_amdgcn_s_getreg((3 << 11) | 20) & 0xFu; }
; __global__ void __launch_bounds__(NTHREADS) mega_kernel(Params p_) {
;     ...
;         if (coop && ph + 1 < ph_hi) {
;             if (ph == 0) {
;                 cg::this_grid().sync();
;                 volatile LAS unsigned* st_ = (volatile LAS unsigned*)(F.lds + 131072 + 64);
;                 if (threadIdx.x == 0) {
;                     unsigned* bar_ = (unsigned*)F.ws; bool ok_ = (gridDim.x % 8u) == 0u;
;                     for (unsigned j = 0; j < 16; ++j) { const unsigned c_ = xb_ld(&bar_[XB_XCNT(j)]); ok_ = ok_ && (c_ == (j < 8u ? gridDim.x / 8u : 0u)); }
;                     const unsigned x_ = xb_xcc_id();
;                     st_[3] = (ok_ && x_ < 8u && st_[2] < gridDim.x / 8u) ? (st_[2] * 8u + x_) : blockIdx.x;
;                 }
;                 __syncthreads();
;             }
;             else { XcdBarrier xb_; xb_.bar = (unsigned*)F.ws; xb_.x = xb_xcc_id(); xb_.st = (volatile LAS unsigned*)(F.lds + 131072 + 64); xcd_barrier(xb_); if (SYNC2) xcd_barrier(xb_); }
.LBB0_790:
	s_andn2_saveexec_b64 s[8:9], s[8:9]
	s_cbranch_execz .LBB0_1139
	v_readlane_b32 s8, v255, 62
	v_readlane_b32 s9, v254, 24
	s_cmp_eq_u32 s8, 0
	s_cbranch_scc1 .Lxb_global
	s_cmpk_lg_i32 s82, 0x100
	s_cbranch_scc1 .Lxb_global
	s_lshr_b32 s8, 0x6ce, s9
	s_bitcmp1_b32 s8, 0
	s_cbranch_scc1 .Lxb_local
	s_cmp_lg_u32 s9, 8
	s_cbranch_scc1 .Lxb_global
	v_readlane_b32 s8, v254, 25
	v_readlane_b32 s10, v254, 27
	s_cmp_lg_u32 s8, 1
	s_cbranch_scc1 .Lxb_local
	s_cmp_eq_u32 s10, 0
	s_cbranch_scc1 .Lxb_local
